# hand-written E1 norm pass for layer 0 (f32 sources), loads of an iteration in flight together
# baseline (speedup 1.0000x reference)
.LBB0_581:
.LBB0_582:
	v_mov_b32_e32 v0, v160
	s_and_b64 vcc, exec, s[36:37]
	s_cbranch_vccnz .LBB0_589
	v_lshlrev_b32_e32 v96, 4, v204
	v_lshlrev_b32_e32 v97, 5, v204
	v_readlane_b32 s14, v243, 0
	v_readlane_b32 s38, v247, 30
	v_readlane_b32 s39, v247, 31
	s_nop 7
	global_load_dwordx4 v[64:67], v97, s[38:39]
	global_load_dwordx4 v[68:71], v97, s[38:39] offset:16
	global_load_dwordx4 v[72:75], v97, s[38:39] offset:2048
	global_load_dwordx4 v[76:79], v97, s[38:39] offset:2064
	s_mov_b32 s26, 0x3a800000
.Le1a_loop:
	s_cmp_lt_u32 s14, 0x8000
	s_cbranch_scc0 .Le1a_ctx
	v_readlane_b32 s0, v247, 18
	v_readlane_b32 s1, v247, 19
	s_mov_b32 s38, s14
	s_lshr_b32 s15, s14, 12
	s_branch .Le1a_adr
.Le1a_ctx:
	v_readlane_b32 s0, v247, 22
	v_readlane_b32 s1, v247, 23
	s_sub_u32 s38, s14, 0x8000
	s_mov_b32 s15, 8
.Le1a_adr:
	s_nop 3
	s_lshr_b32 s39, s38, 20
	s_lshl_b32 s38, s38, 12
	s_add_u32 s0, s0, s38
	s_addc_u32 s1, s1, s39
	s_add_u32 s2, s0, 0x1000
	s_addc_u32 s3, s1, 0
	s_add_u32 s6, s0, 0x2000
	s_addc_u32 s7, s1, 0
	s_add_u32 s8, s0, 0x3000
	s_addc_u32 s9, s1, 0
	global_load_dwordx4 v[100:103], v97, s[0:1]
	global_load_dwordx4 v[104:107], v97, s[0:1] offset:16
	global_load_dwordx4 v[108:111], v97, s[0:1] offset:2048
	global_load_dwordx4 v[112:115], v97, s[0:1] offset:2064
	global_load_dwordx4 v[116:119], v97, s[2:3]
	global_load_dwordx4 v[120:123], v97, s[2:3] offset:16
	global_load_dwordx4 v[124:127], v97, s[2:3] offset:2048
	global_load_dwordx4 v[128:131], v97, s[2:3] offset:2064
	global_load_dwordx4 v[132:135], v97, s[6:7]
	global_load_dwordx4 v[136:139], v97, s[6:7] offset:16
	global_load_dwordx4 v[140:143], v97, s[6:7] offset:2048
	global_load_dwordx4 v[144:147], v97, s[6:7] offset:2064
	global_load_dwordx4 v[148:151], v97, s[8:9]
	global_load_dwordx4 v[152:155], v97, s[8:9] offset:16
	global_load_dwordx4 v[156:159], v97, s[8:9] offset:2048
	global_load_dwordx4 v[164:167], v97, s[8:9] offset:2064
	s_mul_i32 s38, s15, 0x6000
	s_add_u32 s12, s30, s38
	s_addc_u32 s13, s31, 0
	s_add_u32 s8, s12, 0x1000
	s_addc_u32 s9, s13, 0
	global_load_dwordx4 v[32:35], v97, s[8:9]
	global_load_dwordx4 v[36:39], v97, s[8:9] offset:16
	global_load_dwordx4 v[40:43], v97, s[8:9] offset:2048
	global_load_dwordx4 v[44:47], v97, s[8:9] offset:2064
	global_load_dwordx4 v[48:51], v97, s[12:13]
	global_load_dwordx4 v[52:55], v97, s[12:13] offset:16
	global_load_dwordx4 v[56:59], v97, s[12:13] offset:2048
	global_load_dwordx4 v[60:63], v97, s[12:13] offset:2064
	s_lshl_b32 s38, s14, 11
	s_add_u32 s4, s84, 0x4b00000
	s_addc_u32 s5, s85, 0
	s_add_u32 s4, s4, s38
	s_addc_u32 s5, s5, 0
	s_add_u32 s6, s4, 0x1000
	s_addc_u32 s7, s5, 0
	s_waitcnt vmcnt(8)
	v_mul_f32_e32 v80, v100, v100
	v_mul_f32_e32 v81, v116, v116
	v_mul_f32_e32 v82, v132, v132
	v_mul_f32_e32 v83, v148, v148
	v_fmac_f32_e32 v80, v101, v101
	v_fmac_f32_e32 v81, v117, v117
	v_fmac_f32_e32 v82, v133, v133
	v_fmac_f32_e32 v83, v149, v149
	v_fmac_f32_e32 v80, v102, v102
	v_fmac_f32_e32 v81, v118, v118
	v_fmac_f32_e32 v82, v134, v134
	v_fmac_f32_e32 v83, v150, v150
	v_fmac_f32_e32 v80, v103, v103
	v_fmac_f32_e32 v81, v119, v119
	v_fmac_f32_e32 v82, v135, v135
	v_fmac_f32_e32 v83, v151, v151
	v_fmac_f32_e32 v80, v104, v104
	v_fmac_f32_e32 v81, v120, v120
	v_fmac_f32_e32 v82, v136, v136
	v_fmac_f32_e32 v83, v152, v152
	v_fmac_f32_e32 v80, v105, v105
	v_fmac_f32_e32 v81, v121, v121
	v_fmac_f32_e32 v82, v137, v137
	v_fmac_f32_e32 v83, v153, v153
	v_fmac_f32_e32 v80, v106, v106
	v_fmac_f32_e32 v81, v122, v122
	v_fmac_f32_e32 v82, v138, v138
	v_fmac_f32_e32 v83, v154, v154
	v_fmac_f32_e32 v80, v107, v107
	v_fmac_f32_e32 v81, v123, v123
	v_fmac_f32_e32 v82, v139, v139
	v_fmac_f32_e32 v83, v155, v155
	v_fmac_f32_e32 v80, v108, v108
	v_fmac_f32_e32 v81, v124, v124
	v_fmac_f32_e32 v82, v140, v140
	v_fmac_f32_e32 v83, v156, v156
	v_fmac_f32_e32 v80, v109, v109
	v_fmac_f32_e32 v81, v125, v125
	v_fmac_f32_e32 v82, v141, v141
	v_fmac_f32_e32 v83, v157, v157
	v_fmac_f32_e32 v80, v110, v110
	v_fmac_f32_e32 v81, v126, v126
	v_fmac_f32_e32 v82, v142, v142
	v_fmac_f32_e32 v83, v158, v158
	v_fmac_f32_e32 v80, v111, v111
	v_fmac_f32_e32 v81, v127, v127
	v_fmac_f32_e32 v82, v143, v143
	v_fmac_f32_e32 v83, v159, v159
	v_fmac_f32_e32 v80, v112, v112
	v_fmac_f32_e32 v81, v128, v128
	v_fmac_f32_e32 v82, v144, v144
	v_fmac_f32_e32 v83, v164, v164
	v_fmac_f32_e32 v80, v113, v113
	v_fmac_f32_e32 v81, v129, v129
	v_fmac_f32_e32 v82, v145, v145
	v_fmac_f32_e32 v83, v165, v165
	v_fmac_f32_e32 v80, v114, v114
	v_fmac_f32_e32 v81, v130, v130
	v_fmac_f32_e32 v82, v146, v146
	v_fmac_f32_e32 v83, v166, v166
	v_fmac_f32_e32 v80, v115, v115
	v_fmac_f32_e32 v81, v131, v131
	v_fmac_f32_e32 v82, v147, v147
	v_fmac_f32_e32 v83, v167, v167
	v_add_f32_dpp v80, v80, v80 quad_perm:[1,0,3,2] row_mask:0xf bank_mask:0xf
	v_add_f32_dpp v81, v81, v81 quad_perm:[1,0,3,2] row_mask:0xf bank_mask:0xf
	v_add_f32_dpp v82, v82, v82 quad_perm:[1,0,3,2] row_mask:0xf bank_mask:0xf
	v_add_f32_dpp v83, v83, v83 quad_perm:[1,0,3,2] row_mask:0xf bank_mask:0xf
	s_nop 0
	v_add_f32_dpp v80, v80, v80 quad_perm:[2,3,0,1] row_mask:0xf bank_mask:0xf
	v_add_f32_dpp v81, v81, v81 quad_perm:[2,3,0,1] row_mask:0xf bank_mask:0xf
	v_add_f32_dpp v82, v82, v82 quad_perm:[2,3,0,1] row_mask:0xf bank_mask:0xf
	v_add_f32_dpp v83, v83, v83 quad_perm:[2,3,0,1] row_mask:0xf bank_mask:0xf
	s_nop 0
	v_add_f32_dpp v80, v80, v80 row_half_mirror row_mask:0xf bank_mask:0xf
	v_add_f32_dpp v81, v81, v81 row_half_mirror row_mask:0xf bank_mask:0xf
	v_add_f32_dpp v82, v82, v82 row_half_mirror row_mask:0xf bank_mask:0xf
	v_add_f32_dpp v83, v83, v83 row_half_mirror row_mask:0xf bank_mask:0xf
	s_nop 0
	v_add_f32_dpp v80, v80, v80 row_mirror row_mask:0xf bank_mask:0xf
	v_add_f32_dpp v81, v81, v81 row_mirror row_mask:0xf bank_mask:0xf
	v_add_f32_dpp v82, v82, v82 row_mirror row_mask:0xf bank_mask:0xf
	v_add_f32_dpp v83, v83, v83 row_mirror row_mask:0xf bank_mask:0xf
	s_nop 0
	v_add_f32_dpp v80, v80, v80 row_bcast:15 row_mask:0xa bank_mask:0xf
	v_add_f32_dpp v81, v81, v81 row_bcast:15 row_mask:0xa bank_mask:0xf
	v_add_f32_dpp v82, v82, v82 row_bcast:15 row_mask:0xa bank_mask:0xf
	v_add_f32_dpp v83, v83, v83 row_bcast:15 row_mask:0xa bank_mask:0xf
	s_nop 0
	v_add_f32_dpp v80, v80, v80 row_bcast:31 row_mask:0xc bank_mask:0xf
	v_add_f32_dpp v81, v81, v81 row_bcast:31 row_mask:0xc bank_mask:0xf
	v_add_f32_dpp v82, v82, v82 row_bcast:31 row_mask:0xc bank_mask:0xf
	v_add_f32_dpp v83, v83, v83 row_bcast:31 row_mask:0xc bank_mask:0xf
	s_nop 0
	v_mov_b32_e32 v92, 0x358637bd
	s_nop 0
	v_fma_f32 v80, v80, s26, v92
	v_fma_f32 v81, v81, s26, v92
	v_fma_f32 v82, v82, s26, v92
	v_fma_f32 v83, v83, s26, v92
	v_rsq_f32_e32 v80, v80
	v_rsq_f32_e32 v81, v81
	v_rsq_f32_e32 v82, v82
	v_rsq_f32_e32 v83, v83
	s_nop 1
	v_readlane_b32 s16, v80, 63
	v_readlane_b32 s17, v81, 63
	v_readlane_b32 s18, v82, 63
	v_readlane_b32 s19, v83, 63
	s_waitcnt vmcnt(0)
	v_add_f32_e32 v32, 1.0, v32
	v_add_f32_e32 v33, 1.0, v33
	v_add_f32_e32 v34, 1.0, v34
	v_add_f32_e32 v35, 1.0, v35
	v_add_f32_e32 v36, 1.0, v36
	v_add_f32_e32 v37, 1.0, v37
	v_add_f32_e32 v38, 1.0, v38
	v_add_f32_e32 v39, 1.0, v39
	v_add_f32_e32 v40, 1.0, v40
	v_add_f32_e32 v41, 1.0, v41
	v_add_f32_e32 v42, 1.0, v42
	v_add_f32_e32 v43, 1.0, v43
	v_add_f32_e32 v44, 1.0, v44
	v_add_f32_e32 v45, 1.0, v45
	v_add_f32_e32 v46, 1.0, v46
	v_add_f32_e32 v47, 1.0, v47
	v_mul_f32_e32 v32, v64, v32
	v_mul_f32_e32 v33, v65, v33
	v_mul_f32_e32 v34, v66, v34
	v_mul_f32_e32 v35, v67, v35
	v_mul_f32_e32 v36, v68, v36
	v_mul_f32_e32 v37, v69, v37
	v_mul_f32_e32 v38, v70, v38
	v_mul_f32_e32 v39, v71, v39
	v_mul_f32_e32 v40, v72, v40
	v_mul_f32_e32 v41, v73, v41
	v_mul_f32_e32 v42, v74, v42
	v_mul_f32_e32 v43, v75, v43
	v_mul_f32_e32 v44, v76, v44
	v_mul_f32_e32 v45, v77, v45
	v_mul_f32_e32 v46, v78, v46
	v_mul_f32_e32 v47, v79, v47
	v_mul_f32_e32 v100, s16, v100
	v_mul_f32_e32 v101, s16, v101
	v_fma_f32 v100, v100, v32, v48
	v_fma_f32 v101, v101, v33, v49
	v_cvt_pk_bf16_f32 v0, v100, v101
	v_mul_f32_e32 v102, s16, v102
	v_mul_f32_e32 v103, s16, v103
	v_fma_f32 v102, v102, v34, v50
	v_fma_f32 v103, v103, v35, v51
	v_cvt_pk_bf16_f32 v1, v102, v103
	v_mul_f32_e32 v104, s16, v104
	v_mul_f32_e32 v105, s16, v105
	v_fma_f32 v104, v104, v36, v52
	v_fma_f32 v105, v105, v37, v53
	v_cvt_pk_bf16_f32 v2, v104, v105
	v_mul_f32_e32 v106, s16, v106
	v_mul_f32_e32 v107, s16, v107
	v_fma_f32 v106, v106, v38, v54
	v_fma_f32 v107, v107, v39, v55
	v_cvt_pk_bf16_f32 v3, v106, v107
	global_store_dwordx4 v96, v[0:3], s[4:5]
	v_mul_f32_e32 v108, s16, v108
	v_mul_f32_e32 v109, s16, v109
	v_fma_f32 v108, v108, v40, v56
	v_fma_f32 v109, v109, v41, v57
	v_cvt_pk_bf16_f32 v4, v108, v109
	v_mul_f32_e32 v110, s16, v110
	v_mul_f32_e32 v111, s16, v111
	v_fma_f32 v110, v110, v42, v58
	v_fma_f32 v111, v111, v43, v59
	v_cvt_pk_bf16_f32 v5, v110, v111
	v_mul_f32_e32 v112, s16, v112
	v_mul_f32_e32 v113, s16, v113
	v_fma_f32 v112, v112, v44, v60
	v_fma_f32 v113, v113, v45, v61
	v_cvt_pk_bf16_f32 v6, v112, v113
	v_mul_f32_e32 v114, s16, v114
	v_mul_f32_e32 v115, s16, v115
	v_fma_f32 v114, v114, v46, v62
	v_fma_f32 v115, v115, v47, v63
	v_cvt_pk_bf16_f32 v7, v114, v115
	global_store_dwordx4 v96, v[4:7], s[4:5] offset:1024
	v_mul_f32_e32 v116, s17, v116
	v_mul_f32_e32 v117, s17, v117
	v_fma_f32 v116, v116, v32, v48
	v_fma_f32 v117, v117, v33, v49
	v_cvt_pk_bf16_f32 v8, v116, v117
	v_mul_f32_e32 v118, s17, v118
	v_mul_f32_e32 v119, s17, v119
	v_fma_f32 v118, v118, v34, v50
	v_fma_f32 v119, v119, v35, v51
	v_cvt_pk_bf16_f32 v9, v118, v119
	v_mul_f32_e32 v120, s17, v120
	v_mul_f32_e32 v121, s17, v121
	v_fma_f32 v120, v120, v36, v52
	v_fma_f32 v121, v121, v37, v53
	v_cvt_pk_bf16_f32 v10, v120, v121
	v_mul_f32_e32 v122, s17, v122
	v_mul_f32_e32 v123, s17, v123
	v_fma_f32 v122, v122, v38, v54
	v_fma_f32 v123, v123, v39, v55
	v_cvt_pk_bf16_f32 v11, v122, v123
	global_store_dwordx4 v96, v[8:11], s[4:5] offset:2048
	v_mul_f32_e32 v124, s17, v124
	v_mul_f32_e32 v125, s17, v125
	v_fma_f32 v124, v124, v40, v56
	v_fma_f32 v125, v125, v41, v57
	v_cvt_pk_bf16_f32 v12, v124, v125
	v_mul_f32_e32 v126, s17, v126
	v_mul_f32_e32 v127, s17, v127
	v_fma_f32 v126, v126, v42, v58
	v_fma_f32 v127, v127, v43, v59
	v_cvt_pk_bf16_f32 v13, v126, v127
	v_mul_f32_e32 v128, s17, v128
	v_mul_f32_e32 v129, s17, v129
	v_fma_f32 v128, v128, v44, v60
	v_fma_f32 v129, v129, v45, v61
	v_cvt_pk_bf16_f32 v14, v128, v129
	v_mul_f32_e32 v130, s17, v130
	v_mul_f32_e32 v131, s17, v131
	v_fma_f32 v130, v130, v46, v62
	v_fma_f32 v131, v131, v47, v63
	v_cvt_pk_bf16_f32 v15, v130, v131
	global_store_dwordx4 v96, v[12:15], s[4:5] offset:3072
	v_mul_f32_e32 v132, s18, v132
	v_mul_f32_e32 v133, s18, v133
	v_fma_f32 v132, v132, v32, v48
	v_fma_f32 v133, v133, v33, v49
	v_cvt_pk_bf16_f32 v16, v132, v133
	v_mul_f32_e32 v134, s18, v134
	v_mul_f32_e32 v135, s18, v135
	v_fma_f32 v134, v134, v34, v50
	v_fma_f32 v135, v135, v35, v51
	v_cvt_pk_bf16_f32 v17, v134, v135
	v_mul_f32_e32 v136, s18, v136
	v_mul_f32_e32 v137, s18, v137
	v_fma_f32 v136, v136, v36, v52
	v_fma_f32 v137, v137, v37, v53
	v_cvt_pk_bf16_f32 v18, v136, v137
	v_mul_f32_e32 v138, s18, v138
	v_mul_f32_e32 v139, s18, v139
	v_fma_f32 v138, v138, v38, v54
	v_fma_f32 v139, v139, v39, v55
	v_cvt_pk_bf16_f32 v19, v138, v139
	global_store_dwordx4 v96, v[16:19], s[6:7]
	v_mul_f32_e32 v140, s18, v140
	v_mul_f32_e32 v141, s18, v141
	v_fma_f32 v140, v140, v40, v56
	v_fma_f32 v141, v141, v41, v57
	v_cvt_pk_bf16_f32 v20, v140, v141
	v_mul_f32_e32 v142, s18, v142
	v_mul_f32_e32 v143, s18, v143
	v_fma_f32 v142, v142, v42, v58
	v_fma_f32 v143, v143, v43, v59
	v_cvt_pk_bf16_f32 v21, v142, v143
	v_mul_f32_e32 v144, s18, v144
	v_mul_f32_e32 v145, s18, v145
	v_fma_f32 v144, v144, v44, v60
	v_fma_f32 v145, v145, v45, v61
	v_cvt_pk_bf16_f32 v22, v144, v145
	v_mul_f32_e32 v146, s18, v146
	v_mul_f32_e32 v147, s18, v147
	v_fma_f32 v146, v146, v46, v62
	v_fma_f32 v147, v147, v47, v63
	v_cvt_pk_bf16_f32 v23, v146, v147
	global_store_dwordx4 v96, v[20:23], s[6:7] offset:1024
	v_mul_f32_e32 v148, s19, v148
	v_mul_f32_e32 v149, s19, v149
	v_fma_f32 v148, v148, v32, v48
	v_fma_f32 v149, v149, v33, v49
	v_cvt_pk_bf16_f32 v24, v148, v149
	v_mul_f32_e32 v150, s19, v150
	v_mul_f32_e32 v151, s19, v151
	v_fma_f32 v150, v150, v34, v50
	v_fma_f32 v151, v151, v35, v51
	v_cvt_pk_bf16_f32 v25, v150, v151
	v_mul_f32_e32 v152, s19, v152
	v_mul_f32_e32 v153, s19, v153
	v_fma_f32 v152, v152, v36, v52
	v_fma_f32 v153, v153, v37, v53
	v_cvt_pk_bf16_f32 v26, v152, v153
	v_mul_f32_e32 v154, s19, v154
	v_mul_f32_e32 v155, s19, v155
	v_fma_f32 v154, v154, v38, v54
	v_fma_f32 v155, v155, v39, v55
	v_cvt_pk_bf16_f32 v27, v154, v155
	global_store_dwordx4 v96, v[24:27], s[6:7] offset:2048
	v_mul_f32_e32 v156, s19, v156
	v_mul_f32_e32 v157, s19, v157
	v_fma_f32 v156, v156, v40, v56
	v_fma_f32 v157, v157, v41, v57
	v_cvt_pk_bf16_f32 v28, v156, v157
	v_mul_f32_e32 v158, s19, v158
	v_mul_f32_e32 v159, s19, v159
	v_fma_f32 v158, v158, v42, v58
	v_fma_f32 v159, v159, v43, v59
	v_cvt_pk_bf16_f32 v29, v158, v159
	v_mul_f32_e32 v164, s19, v164
	v_mul_f32_e32 v165, s19, v165
	v_fma_f32 v164, v164, v44, v60
	v_fma_f32 v165, v165, v45, v61
	v_cvt_pk_bf16_f32 v30, v164, v165
	v_mul_f32_e32 v166, s19, v166
	v_mul_f32_e32 v167, s19, v167
	v_fma_f32 v166, v166, v46, v62
	v_fma_f32 v167, v167, v47, v63
	v_cvt_pk_bf16_f32 v31, v166, v167
	global_store_dwordx4 v96, v[28:31], s[6:7] offset:3072
	s_add_u32 s14, s14, s24
	s_cmp_lt_u32 s14, 0x8800
	s_cbranch_scc1 .Le1a_loop
	v_readlane_b32 s10, v242, 3
	v_readlane_b32 s11, v242, 4
